# post_phase: conv-weight / r_k / ln gain+bias parameter loads issued with the row loads (fresh registers + copies) on top of the norm and pre_phase load hoists
# baseline (speedup 1.0000x reference)
.LBB0_196:
	s_or_b64 exec, exec, s[24:25]
	v_add_u32_e32 v2, s29, v81
	v_cmp_lt_i32_e32 vcc, s91, v2
	s_waitcnt lgkmcnt(0)
	s_barrier
	s_and_saveexec_b64 s[24:25], vcc
	s_xor_b64 s[24:25], exec, s[24:25]
	v_add_u32_e32 v0, 0xffffff00, v2
	v_lshlrev_b32_e32 v2, 6, v2
	v_lshrrev_b32_e32 v3, 6, v0
	v_and_or_b32 v2, v2, s96, v3
	v_cndmask_b32_e64 v0, v2, v0, s[40:41]
	v_add_u32_e32 v0, s28, v0
	s_andn2_saveexec_b64 s[24:25], s[24:25]
	v_add_u32_e32 v0, s13, v2
	s_or_b64 exec, exec, s[24:25]
	v_mov_b64_e32 v[2:3], s[16:17]
	v_mad_i64_i32 v[2:3], s[24:25], v0, s69, v[2:3]
	v_lshl_add_u64 v[2:3], v[52:53], 1, v[2:3]
	v_add_co_u32_e32 v2, vcc, 0x1000, v2
	s_nop 1
	v_addc_co_u32_e32 v3, vcc, 0, v3, vcc
	global_load_dwordx4 v[6:9], v[2:3], off offset:1024
	v_add_u32_e32 v2, s29, v82
	v_cmp_lt_i32_e32 vcc, s91, v2
	s_and_saveexec_b64 s[24:25], vcc
	s_xor_b64 s[24:25], exec, s[24:25]
	v_add_u32_e32 v0, 0xffffff00, v2
	v_lshlrev_b32_e32 v2, 6, v2
	v_lshrrev_b32_e32 v3, 6, v0
	v_and_or_b32 v2, v2, s96, v3
	v_cndmask_b32_e64 v0, v2, v0, s[40:41]
	v_add_u32_e32 v0, s28, v0
	s_andn2_saveexec_b64 s[24:25], s[24:25]
	v_add_u32_e32 v0, s13, v2
	s_or_b64 exec, exec, s[24:25]
	v_mov_b64_e32 v[2:3], s[16:17]
	v_mad_i64_i32 v[2:3], s[24:25], v0, s69, v[2:3]
	v_lshl_add_u64 v[2:3], v[54:55], 1, v[2:3]
	v_add_co_u32_e32 v2, vcc, 0x1000, v2
	v_add_u32_e32 v0, s29, v79
	s_nop 0
	v_addc_co_u32_e32 v3, vcc, 0, v3, vcc
	global_load_dwordx4 v[2:5], v[2:3], off offset:1024
	s_movk_i32 s24, 0x100
	v_cmp_gt_i32_e64 s[48:49], s24, v0
	v_cmp_lt_i32_e32 vcc, s91, v0
	s_and_saveexec_b64 s[24:25], vcc
	s_xor_b64 s[24:25], exec, s[24:25]
	v_add_u32_e32 v10, 0xffffff00, v0
	v_lshlrev_b32_e32 v11, 6, v0
	v_lshrrev_b32_e32 v12, 6, v10
	v_and_or_b32 v11, v11, s96, v12
	v_cndmask_b32_e64 v10, v11, v10, s[40:41]
	v_add_u32_e32 v64, s28, v10
	s_andn2_saveexec_b64 s[24:25], s[24:25]
	v_add_u32_e32 v64, s13, v0
	s_or_b64 exec, exec, s[24:25]
	v_and_b32_e32 v11, 0x7fffffc0, v0
	v_cndmask_b32_e64 v10, v11, 0, s[48:49]
	v_cmp_gt_i32_e32 vcc, v0, v10
	s_nop 1
	v_subbrev_co_u32_e64 v12, s[50:51], 0, v0, vcc
	v_cmp_lt_i32_e64 s[50:51], s91, v12
	s_and_saveexec_b64 s[24:25], s[50:51]
	s_xor_b64 s[24:25], exec, s[24:25]
	v_add_u32_e32 v10, 0xffffff00, v12
	v_lshlrev_b32_e32 v12, 6, v12
	v_lshrrev_b32_e32 v13, 6, v10
	v_and_or_b32 v12, v12, s96, v13
	v_cndmask_b32_e64 v10, v12, v10, s[40:41]
	v_add_u32_e32 v10, s28, v10
	s_andn2_saveexec_b64 s[24:25], s[24:25]
	v_add_u32_e32 v10, s13, v12
	s_or_b64 exec, exec, s[24:25]
	v_add_u32_e32 v11, 64, v11
	v_mov_b32_e32 v12, 0x100
	v_cndmask_b32_e64 v11, v11, v12, s[48:49]
	v_add_u32_e32 v12, 1, v0
	v_cmp_lt_i32_e64 s[48:49], v12, v11
	s_nop 1
	v_cndmask_b32_e64 v11, v0, v12, s[48:49]
	v_cmp_lt_i32_e64 s[50:51], s91, v11
	s_and_saveexec_b64 s[24:25], s[50:51]
	s_xor_b64 s[24:25], exec, s[24:25]
	v_add_u32_e32 v0, 0xffffff00, v11
	v_lshlrev_b32_e32 v11, 6, v11
	v_lshrrev_b32_e32 v12, 6, v0
	v_and_or_b32 v11, v11, s96, v12
	v_cndmask_b32_e64 v0, v11, v0, s[40:41]
	v_add_u32_e32 v0, s28, v0
	s_andn2_saveexec_b64 s[24:25], s[24:25]
	v_add_u32_e32 v0, s13, v11
	s_or_b64 exec, exec, s[24:25]
	global_load_dwordx4 v[106:109], v[56:57], off offset:1040
	global_load_dwordx4 v[110:113], v[56:57], off offset:1024
	global_load_dwordx4 v[114:117], v[56:57], off offset:16
	global_load_dwordx4 v[118:121], v[56:57], off
	global_load_dwordx4 v[122:125], v[56:57], off offset:2064
	global_load_dwordx4 v[126:129], v[56:57], off offset:2048
	v_mad_i64_i32 v[12:13], s[24:25], v64, s69, v[58:59]
	global_load_dwordx4 v[26:29], v[12:13], off
	global_load_dwordx4 v[30:33], v[12:13], off offset:512
	global_load_dwordx4 v[34:37], v[12:13], off offset:1024
	v_mad_i64_i32 v[10:11], s[24:25], v10, s69, v[58:59]
	v_mad_i64_i32 v[18:19], s[24:25], v0, s69, v[58:59]
	global_load_dwordx4 v[14:17], v[10:11], off offset:512
	s_nop 0
	global_load_dwordx4 v[10:13], v[10:11], off offset:1024
	s_nop 0
	global_load_dwordx4 v[22:25], v[18:19], off offset:512
	s_nop 0
	global_load_dwordx4 v[18:21], v[18:19], off offset:1024
	v_cndmask_b32_e64 v67, 0, 1.0, s[48:49]
	v_cndmask_b32_e64 v66, 0, 1.0, vcc
	v_ashrrev_i32_e32 v65, 31, v64
	s_waitcnt vmcnt(6)
	v_lshlrev_b32_e32 v93, 16, v26
	s_waitcnt vmcnt(5)
	v_lshlrev_b32_e32 v38, 16, v30
	s_waitcnt vmcnt(4)
	v_lshlrev_b32_e32 v39, 16, v34
	v_and_b32_e32 v100, 0xffff0000, v26
	v_lshlrev_b32_e32 v90, 16, v27
	v_and_b32_e32 v77, 0xffff0000, v27
	v_lshlrev_b32_e32 v74, 16, v28
	v_and_b32_e32 v70, 0xffff0000, v28
	v_lshlrev_b32_e32 v68, 16, v29
	v_and_b32_e32 v0, 0xffff0000, v29
	v_and_b32_e32 v101, 0xffff0000, v34
	v_and_b32_e32 v102, 0xffff0000, v30
	v_lshlrev_b32_e32 v103, 16, v31
	v_lshlrev_b32_e32 v104, 16, v35
	v_and_b32_e32 v91, 0xffff0000, v35
	v_and_b32_e32 v92, 0xffff0000, v31
	v_lshlrev_b32_e32 v88, 16, v32
	v_lshlrev_b32_e32 v89, 16, v36
	v_and_b32_e32 v75, 0xffff0000, v36
	v_and_b32_e32 v76, 0xffff0000, v32
	v_lshlrev_b32_e32 v72, 16, v33
	v_lshlrev_b32_e32 v73, 16, v37
	v_and_b32_e32 v69, 0xffff0000, v37
	v_and_b32_e32 v71, 0xffff0000, v33
	v_mov_b64_e32 v[26:27], v[106:107]
	v_mov_b64_e32 v[28:29], v[108:109]
	v_mov_b64_e32 v[34:35], v[110:111]
	v_mov_b64_e32 v[36:37], v[112:113]
	v_mul_f32_e32 v105, v39, v38
	v_mov_b64_e32 v[30:31], v[114:115]
	v_mov_b64_e32 v[32:33], v[116:117]
	v_mov_b64_e32 v[42:43], v[118:119]
	v_mov_b64_e32 v[44:45], v[120:121]
	v_mov_b64_e32 v[38:39], v[122:123]
	v_mov_b64_e32 v[40:41], v[124:125]
	v_mov_b64_e32 v[46:47], v[126:127]
	v_mov_b64_e32 v[48:49], v[128:129]
	s_waitcnt vmcnt(1)
	v_lshlrev_b32_e32 v95, 16, v22
	v_lshlrev_b32_e32 v94, 16, v14
	s_waitcnt vmcnt(0)
	v_lshlrev_b32_e32 v97, 16, v18
	v_lshlrev_b32_e32 v96, 16, v10
	v_pk_mul_f32 v[94:95], v[94:95], v[96:97]
	v_and_b32_e32 v97, 0xffff0000, v18
	v_and_b32_e32 v96, 0xffff0000, v10
	v_mul_f32_e32 v18, v91, v92
	s_waitcnt vmcnt(0)
	v_mov_b32_e32 v98, v42
	s_waitcnt vmcnt(0)
	v_mov_b32_e32 v99, v46
	v_pk_mul_f32 v[98:99], v[66:67], v[98:99]
	v_mov_b32_e32 v46, v43
	v_pk_mul_f32 v[94:95], v[98:99], v[94:95]
	v_pk_mul_f32 v[42:43], v[66:67], v[46:47]
	v_fma_f32 v34, v105, v34, v94
	v_add_f32_e32 v34, v34, v95
	v_and_b32_e32 v95, 0xffff0000, v22
	v_and_b32_e32 v94, 0xffff0000, v14
	v_pk_mul_f32 v[46:47], v[94:95], v[96:97]
	v_mul_f32_e32 v93, v34, v93
	v_mul_f32_e32 v34, v101, v102
	v_pk_mul_f32 v[42:43], v[46:47], v[42:43]
	v_mov_b32_e32 v46, v44
	v_fma_f32 v10, v34, v35, v42
	v_add_f32_e32 v10, v10, v43
	v_lshlrev_b32_e32 v35, 16, v23
	v_lshlrev_b32_e32 v34, 16, v15
	v_lshlrev_b32_e32 v43, 16, v19
	v_lshlrev_b32_e32 v42, 16, v11
	v_mov_b32_e32 v47, v48
	v_pk_mul_f32 v[46:47], v[66:67], v[46:47]
	v_pk_mul_f32 v[34:35], v[34:35], v[42:43]
	v_mul_f32_e32 v94, v10, v100
	v_mul_f32_e32 v10, v104, v103
	v_pk_mul_f32 v[34:35], v[34:35], v[46:47]
	v_and_b32_e32 v23, 0xffff0000, v23
	v_fma_f32 v10, v10, v36, v34
	v_add_f32_e32 v10, v10, v35
	v_and_b32_e32 v22, 0xffff0000, v15
	v_and_b32_e32 v15, 0xffff0000, v19
	v_and_b32_e32 v14, 0xffff0000, v11
	v_mov_b32_e32 v48, v45
	v_mul_f32_e32 v34, v10, v90
	v_pk_mul_f32 v[10:11], v[66:67], v[48:49]
	v_pk_mul_f32 v[14:15], v[22:23], v[14:15]
	v_mov_b32_e32 v19, v38
	v_pk_mul_f32 v[10:11], v[14:15], v[10:11]
	v_lshlrev_b32_e32 v15, 16, v20
	v_fma_f32 v10, v18, v37, v10
	v_add_f32_e32 v10, v10, v11
	v_mul_f32_e32 v22, v10, v77
	v_lshlrev_b32_e32 v11, 16, v24
	v_lshlrev_b32_e32 v10, 16, v16
	v_lshlrev_b32_e32 v14, 16, v12
	v_mov_b32_e32 v18, v30
	v_pk_mul_f32 v[18:19], v[66:67], v[18:19]
	v_pk_mul_f32 v[10:11], v[10:11], v[14:15]
	v_mul_f32_e32 v23, v89, v88
	v_pk_mul_f32 v[10:11], v[10:11], v[18:19]
	v_and_b32_e32 v15, 0xffff0000, v20
	v_fma_f32 v10, v23, v26, v10
	v_add_f32_e32 v10, v10, v11
	v_mul_f32_e32 v23, v10, v74
	v_and_b32_e32 v11, 0xffff0000, v24
	v_and_b32_e32 v10, 0xffff0000, v16
	v_and_b32_e32 v14, 0xffff0000, v12
	v_mov_b32_e32 v38, v31
	v_pk_mul_f32 v[18:19], v[66:67], v[38:39]
	v_pk_mul_f32 v[10:11], v[10:11], v[14:15]
	v_mul_f32_e32 v26, v75, v76
	v_pk_mul_f32 v[10:11], v[10:11], v[18:19]
	v_lshlrev_b32_e32 v15, 16, v21
	v_fma_f32 v10, v26, v27, v10
	v_add_f32_e32 v10, v10, v11
	v_mul_f32_e32 v16, v10, v70
	v_lshlrev_b32_e32 v11, 16, v25
	v_lshlrev_b32_e32 v10, 16, v17
	v_lshlrev_b32_e32 v14, 16, v13
	v_mov_b32_e32 v18, v32
	v_mov_b32_e32 v19, v40
	v_pk_mul_f32 v[18:19], v[66:67], v[18:19]
	v_pk_mul_f32 v[10:11], v[10:11], v[14:15]
	v_mul_f32_e32 v12, v73, v72
	v_pk_mul_f32 v[10:11], v[10:11], v[18:19]
	v_and_b32_e32 v15, 0xffff0000, v21
	v_fma_f32 v10, v12, v28, v10
	v_add_f32_e32 v10, v10, v11
	v_mul_f32_e32 v18, v10, v68
	v_and_b32_e32 v11, 0xffff0000, v25
	v_and_b32_e32 v10, 0xffff0000, v17
	v_and_b32_e32 v14, 0xffff0000, v13
	v_mov_b32_e32 v40, v33
	v_pk_mul_f32 v[12:13], v[66:67], v[40:41]
	v_pk_mul_f32 v[10:11], v[10:11], v[14:15]
	v_mul_f32_e32 v19, v69, v71
	v_pk_mul_f32 v[10:11], v[10:11], v[12:13]
	v_lshlrev_b64 v[14:15], 11, v[64:65]
	v_fma_f32 v10, v19, v29, v10
	v_add_f32_e32 v10, v10, v11
	v_lshl_add_u64 v[14:15], v[50:51], 0, v[14:15]
	v_mul_f32_e32 v0, v10, v0
	v_cvt_pk_bf16_f32 v10, v93, v94
	v_cvt_pk_bf16_f32 v11, v34, v22
	v_cvt_pk_bf16_f32 v12, v23, v16
	v_cvt_pk_bf16_f32 v13, v18, v0
	global_store_dwordx4 v[14:15], v[10:13], off
	s_and_saveexec_b64 s[24:25], s[44:45]
	s_cbranch_execz .LBB0_223
	s_mul_hi_i32 s49, s30, 0x1100
	s_mul_i32 s48, s30, 0x1100
	s_mov_b64 s[50:51], 0
	v_mov_b32_e32 v0, v87
	v_mov_b32_e32 v88, v80
	s_branch .LBB0_219
.LBB0_218:
	s_or_b64 exec, exec, s[26:27]
	s_movk_i32 s26, 0xfe80
	v_mad_u64_u32 v[30:31], s[26:27], v11, s26, v[0:1]
	v_ashrrev_i32_e32 v11, 31, v10
	v_lshl_add_u64 v[26:27], s[48:49], 0, v[10:11]
	v_mov_b64_e32 v[18:19], s[18:19]
	v_mov_b64_e32 v[22:23], s[20:21]
	v_ashrrev_i32_e32 v31, 31, v30
	v_mad_u64_u32 v[18:19], s[26:27], v26, s3, v[18:19]
	v_mul_lo_u32 v39, v27, s3
	v_mad_u64_u32 v[22:23], s[26:27], v26, s3, v[22:23]
	v_lshlrev_b64 v[36:37], 1, v[30:31]
	v_add_u32_e32 v19, v39, v19
	v_add_u32_e32 v23, v39, v23
	v_lshl_add_u64 v[18:19], v[18:19], 0, v[36:37]
	v_lshl_add_u64 v[22:23], v[22:23], 0, v[36:37]
	global_load_dwordx4 v[18:21], v[18:19], off
	v_mov_b64_e32 v[28:29], s[60:61]
	global_load_dwordx4 v[22:25], v[22:23], off
	v_mov_b64_e32 v[10:11], s[16:17]
	v_mad_i64_i32 v[10:11], s[26:27], v34, s69, v[10:11]
	v_lshl_add_u64 v[32:33], v[10:11], 0, v[36:37]
	global_load_dwordx4 v[10:13], v[32:33], off offset:1536
	global_load_dwordx4 v[14:17], v[32:33], off offset:2304
	v_lshlrev_b64 v[130:131], 2, v[30:31]
	v_lshl_add_u64 v[132:133], s[52:53], 0, v[130:131]
	v_lshl_add_u64 v[134:135], s[54:55], 0, v[130:131]
	v_lshl_add_u64 v[136:137], s[56:57], 0, v[130:131]
	global_load_dwordx4 v[138:141], v[132:133], off offset:16
	global_load_dwordx4 v[142:145], v[132:133], off
	global_load_dwordx4 v[146:149], v[134:135], off offset:16
	global_load_dwordx4 v[150:153], v[134:135], off
	global_load_dwordx4 v[154:157], v[136:137], off offset:16
	global_load_dwordx4 v[158:161], v[136:137], off
	v_ashrrev_i32_e32 v35, 31, v34
	v_add_u32_e32 v0, 0x1000, v0
	s_waitcnt vmcnt(8)
	v_lshlrev_b32_e32 v66, 16, v22
	v_and_b32_e32 v64, 0xffff0000, v22
	v_lshlrev_b32_e32 v48, 16, v23
	v_and_b32_e32 v46, 0xffff0000, v23
	v_mov_b64_e32 v[22:23], s[58:59]
	v_mad_u64_u32 v[22:23], s[26:27], v26, s3, v[22:23]
	v_mad_u64_u32 v[26:27], s[26:27], v26, s3, v[28:29]
	v_add_u32_e32 v23, v39, v23
	v_add_u32_e32 v27, v39, v27
	v_lshl_add_u64 v[22:23], v[22:23], 0, v[36:37]
	v_lshl_add_u64 v[26:27], v[26:27], 0, v[36:37]
	v_lshlrev_b32_e32 v44, 16, v24
	v_and_b32_e32 v42, 0xffff0000, v24
	v_lshlrev_b32_e32 v40, 16, v25
	v_and_b32_e32 v38, 0xffff0000, v25
	global_load_dwordx4 v[22:25], v[22:23], off
	s_nop 0
	global_load_dwordx4 v[26:29], v[26:27], off
	s_nop 0
	global_load_dwordx4 v[72:75], v[32:33], off offset:3072
	s_waitcnt vmcnt(9)
	v_lshlrev_b32_e32 v33, 16, v14
	v_and_b32_e32 v32, 0xffff0000, v14
	v_lshlrev_b32_e32 v69, 16, v13
	v_lshlrev_b32_e32 v71, 16, v17
	s_waitcnt vmcnt(1)
	v_and_b32_e32 v91, 0xffff0000, v26
	s_waitcnt vmcnt(0)
	v_lshlrev_b32_e32 v65, 16, v72
	v_and_b32_e32 v49, 0xffff0000, v72
	v_lshlrev_b32_e32 v47, 16, v73
	v_and_b32_e32 v45, 0xffff0000, v73
	v_lshlrev_b32_e32 v73, 16, v10
	v_and_b32_e32 v72, 0xffff0000, v10
	v_lshlrev_b32_e32 v43, 16, v74
	v_and_b32_e32 v41, 0xffff0000, v74
	v_lshlrev_b32_e32 v39, 16, v75
	v_and_b32_e32 v89, 0xffff0000, v75
	v_lshlrev_b64 v[74:75], 2, v[30:31]
	v_pk_add_f32 v[72:73], v[72:73], v[32:33]
	v_and_b32_e32 v33, 0xffff0000, v22
	v_lshlrev_b32_e32 v32, 16, v22
	v_lshlrev_b32_e32 v90, 16, v26
	v_lshl_add_u64 v[76:77], s[52:53], 0, v[74:75]
	v_and_b32_e32 v31, 0xffff0000, v18
	v_lshlrev_b32_e32 v30, 16, v18
	v_pk_add_f32 v[32:33], v[32:33], v[90:91]
	v_add_f32_e32 v10, 0, v73
	v_pk_mul_f32 v[94:95], v[32:33], v[30:31]
	v_mov_b64_e32 v[30:31], v[138:139]
	v_mov_b64_e32 v[32:33], v[140:141]
	v_mov_b64_e32 v[90:91], v[142:143]
	v_mov_b64_e32 v[92:93], v[144:145]
	v_add_f32_e32 v10, v72, v10
	v_lshlrev_b32_e32 v18, 16, v27
	s_waitcnt vmcnt(0)
	v_pk_mul_f32 v[76:77], v[90:91], v[94:95]
	s_nop 0
	v_add_f32_e32 v14, 0, v76
	v_add_f32_e32 v22, v77, v14
	v_lshlrev_b32_e32 v77, 16, v15
	v_lshlrev_b32_e32 v91, 16, v11
	v_and_b32_e32 v76, 0xffff0000, v15
	v_and_b32_e32 v90, 0xffff0000, v11
	v_pk_add_f32 v[76:77], v[90:91], v[76:77]
	v_and_b32_e32 v11, 0xffff0000, v19
	v_add_f32_e32 v10, v77, v10
	v_add_f32_e32 v26, v76, v10
	v_lshlrev_b32_e32 v10, 16, v19
	v_and_b32_e32 v15, 0xffff0000, v23
	v_lshlrev_b32_e32 v14, 16, v23
	v_and_b32_e32 v19, 0xffff0000, v27
	v_pk_add_f32 v[14:15], v[14:15], v[18:19]
	v_and_b32_e32 v27, 0xffff0000, v28
	v_pk_mul_f32 v[10:11], v[14:15], v[10:11]
	v_lshlrev_b32_e32 v15, 16, v12
	v_pk_mul_f32 v[10:11], v[92:93], v[10:11]
	v_and_b32_e32 v14, 0xffff0000, v12
	v_add_f32_e32 v10, v10, v22
	v_add_f32_e32 v22, v11, v10
	v_lshlrev_b32_e32 v11, 16, v16
	v_and_b32_e32 v10, 0xffff0000, v16
	v_pk_add_f32 v[18:19], v[14:15], v[10:11]
	v_and_b32_e32 v15, 0xffff0000, v24
	v_add_f32_e32 v10, v19, v26
	v_lshlrev_b32_e32 v14, 16, v24
	v_lshlrev_b32_e32 v26, 16, v28
	v_add_f32_e32 v23, v18, v10
	v_and_b32_e32 v11, 0xffff0000, v20
	v_lshlrev_b32_e32 v10, 16, v20
	v_pk_add_f32 v[14:15], v[14:15], v[26:27]
	v_and_b32_e32 v20, 0xffff0000, v13
	v_pk_mul_f32 v[10:11], v[14:15], v[10:11]
	v_and_b32_e32 v13, 0xffff0000, v25
	v_pk_mul_f32 v[10:11], v[10:11], v[30:31]
	v_lshlrev_b32_e32 v12, 16, v25
	v_add_f32_e32 v10, v10, v22
	v_and_b32_e32 v15, 0xffff0000, v29
	v_lshlrev_b32_e32 v14, 16, v29
	v_add_f32_e32 v16, v11, v10
	v_and_b32_e32 v11, 0xffff0000, v21
	v_lshlrev_b32_e32 v10, 16, v21
	v_pk_add_f32 v[12:13], v[12:13], v[14:15]
	v_lshl_add_u64 v[14:15], s[54:55], 0, v[74:75]
	v_pk_mul_f32 v[10:11], v[12:13], v[10:11]
	v_lshl_add_u64 v[28:29], s[56:57], 0, v[74:75]
	v_pk_mul_f32 v[10:11], v[10:11], v[32:33]
	v_and_b32_e32 v22, 0xffff0000, v17
	v_add_f32_e32 v10, v10, v16
	v_add_f32_e32 v68, v11, v10
	v_mov_b64_e32 v[10:11], v[146:147]
	v_mov_b64_e32 v[12:13], v[148:149]
	v_mov_b64_e32 v[24:25], v[150:151]
	v_mov_b64_e32 v[26:27], v[152:153]
	v_mov_b64_e32 v[14:15], v[154:155]
	v_mov_b64_e32 v[16:17], v[156:157]
	v_mov_b64_e32 v[28:29], v[158:159]
	v_mov_b64_e32 v[30:31], v[160:161]
	v_mov_b32_dpp v70, v68 quad_perm:[1,0,3,2] row_mask:0xf bank_mask:0xf bound_ctrl:1
	v_pk_add_f32 v[32:33], v[68:69], v[70:71]
	v_mov_b32_e32 v70, v77
	v_mov_b32_e32 v21, v33
	v_pk_add_f32 v[20:21], v[20:21], v[22:23]
	v_mov_b32_e32 v71, v73
	v_add_f32_e32 v21, v20, v21
	v_mov_b32_dpp v22, v32 quad_perm:[2,3,0,1] row_mask:0xf bank_mask:0xf bound_ctrl:1
	v_pk_mov_b32 v[76:77], v[18:19], v[76:77] op_sel:[1,0]
	v_add_f32_dpp v21, v21, v21 quad_perm:[1,0,3,2] row_mask:0xf bank_mask:0xf bound_ctrl:1
	s_nop 1
	v_add_f32_dpp v21, v21, v21 quad_perm:[2,3,0,1] row_mask:0xf bank_mask:0xf bound_ctrl:1
	s_nop 1
	v_add_f32_dpp v21, v21, v21 row_half_mirror row_mask:0xf bank_mask:0xf bound_ctrl:1
	v_mul_f32_e32 v23, 0x3c800000, v21
	v_mov_b32_e32 v74, v23
	v_pk_add_f32 v[70:71], v[70:71], v[74:75] op_sel_hi:[1,0] neg_lo:[0,1] neg_hi:[0,1]
	v_fmac_f32_e32 v72, 0xbc800000, v21
	v_pk_mul_f32 v[90:91], v[70:71], v[70:71]
	v_pk_add_f32 v[68:69], v[32:33], v[22:23]
	v_pk_add_f32 v[32:33], v[32:33], v[22:23] neg_lo:[0,1] neg_hi:[0,1]
	v_fma_f32 v23, v72, v72, v91
	v_pk_add_f32 v[74:75], v[76:77], v[74:75] op_sel_hi:[1,0] neg_lo:[0,1] neg_hi:[0,1]
	v_add_f32_e32 v23, v90, v23
	v_pk_mul_f32 v[76:77], v[74:75], v[74:75]
	v_fmac_f32_e32 v18, 0xbc800000, v21
	v_add_f32_e32 v19, v77, v23
	v_add_f32_e32 v19, v76, v19
	v_mov_b32_e32 v76, v33
	v_mov_b32_e32 v77, v18
	v_pk_mul_f32 v[76:77], v[76:77], v[76:77]
	v_fmac_f32_e32 v20, 0xbc800000, v21
	v_add_f32_e32 v19, v77, v19
	v_add_f32_e32 v19, v76, v19
	v_fmac_f32_e32 v19, v20, v20
	v_mov_b32_e32 v21, 0x3a27c5ac
	v_mov_b32_dpp v22, v68 row_half_mirror row_mask:0xf bank_mask:0xf bound_ctrl:1
	v_add_f32_dpp v19, v19, v19 quad_perm:[1,0,3,2] row_mask:0xf bank_mask:0xf bound_ctrl:1
	s_nop 1
	v_add_f32_dpp v19, v19, v19 quad_perm:[2,3,0,1] row_mask:0xf bank_mask:0xf bound_ctrl:1
	s_nop 1
	v_add_f32_dpp v19, v19, v19 row_half_mirror row_mask:0xf bank_mask:0xf bound_ctrl:1
	v_fmamk_f32 v19, v19, 0x3c800000, v21
	v_cmp_gt_f32_e32 vcc, s66, v19
	v_mul_f32_e32 v21, 0x4b800000, v19
	s_nop 0
	v_cndmask_b32_e32 v19, v19, v21, vcc
	v_rsq_f32_e32 v19, v19
	s_nop 0
	v_mul_f32_e32 v21, 0x45800000, v19
	v_cndmask_b32_e32 v23, v19, v21, vcc
	v_pk_add_f32 v[68:69], v[68:69], v[22:23]
	v_pk_mul_f32 v[32:33], v[32:33], v[22:23]
	v_mul_f32_e32 v67, v71, v23
	v_mov_b32_e32 v69, v33
	v_mov_b32_e32 v32, v68
	v_cmp_lt_i32_e32 vcc, 31, v88
	s_or_b64 s[50:51], vcc, s[50:51]
	s_waitcnt vmcnt(2)
	v_mov_b32_e32 v33, v24
	v_pk_mul_f32 v[32:33], v[32:33], v[66:67]
	v_mov_b32_e32 v24, v68
	s_waitcnt vmcnt(0)
	v_add_f32_e32 v19, v28, v33
	v_add_f32_e32 v19, v32, v19
	v_mul_f32_e32 v19, v19, v65
	v_mul_f32_e32 v65, v72, v23
	v_pk_mul_f32 v[24:25], v[24:25], v[64:65]
	s_nop 0
	v_add_f32_e32 v21, v29, v25
	v_add_f32_e32 v21, v24, v21
	v_mul_f32_e32 v21, v21, v49
	v_mul_f32_e32 v49, v70, v23
	v_mov_b32_e32 v24, v68
	v_mov_b32_e32 v25, v26
	v_pk_mul_f32 v[24:25], v[24:25], v[48:49]
	v_mov_b32_e32 v26, v68
	v_add_f32_e32 v22, v30, v25
	v_add_f32_e32 v22, v24, v22
	v_mul_f32_e32 v22, v22, v47
	v_mul_f32_e32 v47, v75, v23
	v_pk_mul_f32 v[24:25], v[26:27], v[46:47]
	s_nop 0
	v_add_f32_e32 v25, v31, v25
	v_add_f32_e32 v24, v24, v25
	v_mul_f32_e32 v26, v24, v45
	v_mul_f32_e32 v45, v74, v23
	v_mov_b32_e32 v24, v68
	v_mov_b32_e32 v25, v10
	v_pk_mul_f32 v[24:25], v[24:25], v[44:45]
	s_nop 0
	v_add_f32_e32 v10, v14, v25
	v_add_f32_e32 v10, v24, v10
	v_mul_f32_e32 v14, v10, v43
	v_mul_f32_e32 v43, v18, v23
	v_mov_b32_e32 v10, v68
	v_pk_mul_f32 v[10:11], v[10:11], v[42:43]
	s_nop 0
	v_add_f32_e32 v11, v15, v11
	v_add_f32_e32 v10, v10, v11
	v_mul_f32_e32 v15, v10, v41
	v_mov_b32_e32 v41, v12
	v_pk_mul_f32 v[10:11], v[68:69], v[40:41]
	v_mov_b32_e32 v69, v13
	v_add_f32_e32 v11, v16, v11
	v_add_f32_e32 v10, v10, v11
	v_mul_f32_e32 v16, v10, v39
	v_mul_f32_e32 v39, v20, v23
	v_pk_mul_f32 v[10:11], v[68:69], v[38:39]
	v_cvt_pk_bf16_f32 v12, v14, v15
	v_lshlrev_b64 v[14:15], 11, v[34:35]
	v_add_f32_e32 v11, v17, v11
	v_add_f32_e32 v10, v10, v11
	v_lshl_add_u64 v[14:15], s[14:15], 0, v[14:15]
	v_mul_f32_e32 v13, v10, v89
	v_cvt_pk_bf16_f32 v10, v19, v21
	v_lshl_add_u64 v[14:15], v[14:15], 0, v[36:37]
	v_cvt_pk_bf16_f32 v11, v22, v26
	v_cvt_pk_bf16_f32 v13, v16, v13
	global_store_dwordx4 v[14:15], v[10:13], off offset:512
	s_nop 1
	v_add_u32_e32 v10, 64, v88
	v_mov_b32_e32 v88, v10
	s_andn2_b64 exec, exec, s[50:51]
	s_cbranch_execz .LBB0_223
